# stackC + NORM and FINAL row loops process two row-pairs per trip (16 loads issued up front)
# speedup vs baseline: 1.0082x; 1.0082x over previous
; __device__ __forceinline__ void final_phase(const Params& p) {
;     ...
;     for (int r0 = gw * RPW; r0 < MTOK; r0 += ngw * RPW) {
;         for (int rr = 0; rr < RPW; rr += 2) {
;             f32x4* xa = (f32x4*)(p.out + (size_t)(r0 + rr) * DM) + lane; f32x4* xb = xa + DM / 4;
;             f32x4 va[4], vb[4]; float sa = 0.f, sb = 0.f;
; #pragma unroll
;             for (int j = 0; j < 4; ++j) { va[j] = __builtin_nontemporal_load(xa + 64 * j); vb[j] = __builtin_nontemporal_load(xb + 64 * j); }
; #pragma unroll
;             for (int j = 0; j < 4; ++j) { sa += (va[j][0] * va[j][0] + va[j][1] * va[j][1]) + (va[j][2] * va[j][2] + va[j][3] * va[j][3]); sb += (vb[j][0] * vb[j][0] + vb[j][1] * vb[j][1]) + (vb[j][2] * vb[j][2] + vb[j][3] * vb[j][3]); }
;             const float ra = rsqrtf(wave_sum(sa, x32a) * (1.0f / DM) + 1e-6f), rb = rsqrtf(wave_sum(sb, x32a) * (1.0f / DM) + 1e-6f);
.LBB0_30:
	global_load_dwordx4 v[46:49], v[54:55], off offset:-4096 nt
	global_load_dwordx4 v[42:45], v[54:55], off nt
	global_load_dwordx4 v[38:41], v[54:55], off offset:-3072 nt
	global_load_dwordx4 v[34:37], v[54:55], off offset:1024 nt
	global_load_dwordx4 v[30:33], v[54:55], off offset:-2048 nt
	global_load_dwordx4 v[26:29], v[54:55], off offset:2048 nt
	global_load_dwordx4 v[22:25], v[54:55], off offset:-1024 nt
	global_load_dwordx4 v[18:21], v[54:55], off offset:3072 nt
	v_lshl_add_u64 v[102:103], v[54:55], 0, s[6:7]
	global_load_dwordx4 v[70:73], v[102:103], off offset:-4096 nt
	global_load_dwordx4 v[74:77], v[102:103], off nt
	global_load_dwordx4 v[78:81], v[102:103], off offset:-3072 nt
	global_load_dwordx4 v[82:85], v[102:103], off offset:1024 nt
	global_load_dwordx4 v[86:89], v[102:103], off offset:-2048 nt
	global_load_dwordx4 v[90:93], v[102:103], off offset:2048 nt
	global_load_dwordx4 v[94:97], v[102:103], off offset:-1024 nt
	global_load_dwordx4 v[98:101], v[102:103], off offset:3072 nt
	s_add_i32 s4, s4, 2
	s_cmp_gt_u32 s4, 13
	s_waitcnt vmcnt(8)
	v_pk_mul_f32 v[56:57], v[48:49], v[48:49]
	v_pk_mul_f32 v[58:59], v[46:47], v[46:47]
	s_waitcnt vmcnt(9)
	v_mul_f32_e32 v51, v22, v22
	v_pk_mov_b32 v[60:61], v[58:59], v[56:57] op_sel:[1,0]
	v_mov_b32_e32 v59, v57
	v_pk_add_f32 v[56:57], v[60:61], v[58:59]
	v_pk_mul_f32 v[58:59], v[44:45], v[44:45]
	v_pk_mul_f32 v[60:61], v[42:43], v[42:43]
	v_pk_add_f32 v[56:57], v[56:57], v[56:57] op_sel:[0,1] op_sel_hi:[1,0]
	v_pk_mov_b32 v[62:63], v[60:61], v[58:59] op_sel:[1,0]
	v_mov_b32_e32 v61, v59
	v_pk_add_f32 v[58:59], v[62:63], v[60:61]
	v_pk_mul_f32 v[60:61], v[40:41], v[40:41]
	v_pk_mul_f32 v[62:63], v[38:39], v[38:39]
	v_mov_b32_e32 v57, v51
	v_pk_mov_b32 v[64:65], v[62:63], v[60:61] op_sel:[1,0]
	v_mov_b32_e32 v63, v61
	v_pk_add_f32 v[60:61], v[64:65], v[62:63]
	v_pk_mul_f32 v[62:63], v[36:37], v[36:37]
	v_pk_mul_f32 v[64:65], v[34:35], v[34:35]
	v_pk_add_f32 v[60:61], v[60:61], v[60:61] op_sel:[0,1] op_sel_hi:[1,0]
	v_pk_mov_b32 v[66:67], v[64:65], v[62:63] op_sel:[1,0]
	v_mov_b32_e32 v65, v63
	v_pk_add_f32 v[62:63], v[66:67], v[64:65]
	v_mul_f32_e32 v64, v23, v23
	v_mov_b32_e32 v61, v64
	v_pk_add_f32 v[56:57], v[56:57], v[60:61]
	v_mul_f32_e32 v60, v31, v31
	v_mul_f32_e32 v65, v24, v24
	v_pk_fma_f32 v[60:61], v[30:31], v[30:31], v[60:61] op_sel_hi:[1,1,0]
	v_mul_f32_e32 v64, v33, v33
	v_mul_f32_e32 v66, v25, v25
	v_mov_b32_e32 v61, v65
	v_pk_fma_f32 v[64:65], v[32:33], v[32:33], v[64:65] op_sel_hi:[1,1,0]
	s_waitcnt vmcnt(8)
	v_mul_f32_e32 v51, v18, v18
	v_mov_b32_e32 v65, v66
	v_pk_add_f32 v[60:61], v[60:61], v[64:65]
	v_mul_f32_e32 v64, v19, v19
	v_pk_add_f32 v[56:57], v[56:57], v[60:61]
	v_pk_add_f32 v[58:59], v[58:59], v[58:59] op_sel:[0,1] op_sel_hi:[1,0]
	v_pk_add_f32 v[60:61], v[62:63], v[62:63] op_sel:[0,1] op_sel_hi:[1,0]
	v_mov_b32_e32 v59, v51
	v_mov_b32_e32 v61, v64
	v_pk_add_f32 v[58:59], v[58:59], v[60:61]
	v_mul_f32_e32 v60, v27, v27
	v_mul_f32_e32 v62, v29, v29
	v_mul_f32_e32 v65, v20, v20
	v_mul_f32_e32 v66, v21, v21
	v_pk_fma_f32 v[60:61], v[26:27], v[26:27], v[60:61] op_sel_hi:[1,1,0]
	v_pk_fma_f32 v[62:63], v[28:29], v[28:29], v[62:63] op_sel_hi:[1,1,0]
	v_mov_b32_e32 v61, v65
	v_mov_b32_e32 v63, v66
	v_pk_add_f32 v[60:61], v[60:61], v[62:63]
	s_nop 0
	v_pk_add_f32 v[58:59], v[58:59], v[60:61]
	v_mov_b32_e32 v61, v56
	v_mov_b32_e32 v60, v58
	v_mov_b32_e32 v56, v59
	v_pk_add_f32 v[56:57], v[60:61], v[56:57]
	ds_swizzle_b32 v59, v57 offset:swizzle(SWAP,1)
	ds_swizzle_b32 v58, v56 offset:swizzle(SWAP,1)
	s_waitcnt lgkmcnt(0)
	v_pk_add_f32 v[56:57], v[56:57], v[58:59]
	ds_swizzle_b32 v59, v57 offset:swizzle(SWAP,2)
	ds_swizzle_b32 v58, v56 offset:swizzle(SWAP,2)
	s_waitcnt lgkmcnt(0)
	v_pk_add_f32 v[56:57], v[56:57], v[58:59]
	ds_swizzle_b32 v59, v57 offset:swizzle(SWAP,4)
	ds_swizzle_b32 v58, v56 offset:swizzle(SWAP,4)
	s_waitcnt lgkmcnt(0)
	v_pk_add_f32 v[56:57], v[56:57], v[58:59]
	ds_swizzle_b32 v59, v57 offset:swizzle(SWAP,8)
	ds_swizzle_b32 v58, v56 offset:swizzle(SWAP,8)
	s_waitcnt lgkmcnt(0)
	v_pk_add_f32 v[56:57], v[56:57], v[58:59]
	ds_swizzle_b32 v59, v57 offset:swizzle(SWAP,16)
	ds_swizzle_b32 v58, v56 offset:swizzle(SWAP,16)
	s_waitcnt lgkmcnt(0)
	v_pk_add_f32 v[56:57], v[56:57], v[58:59]
	ds_bpermute_b32 v59, v1, v57
	ds_bpermute_b32 v58, v1, v56
	s_waitcnt lgkmcnt(0)
; __device__ __forceinline__ void final_phase(const Params& p) {
;     ...
;         for (int rr = 0; rr < RPW; rr += 2) {
;             f32x4* xa = (f32x4*)(p.out + (size_t)(r0 + rr) * DM) + lane; f32x4* xb = xa + DM / 4;
;             f32x4 va[4], vb[4]; float sa = 0.f, sb = 0.f;
; #pragma unroll
;             for (int j = 0; j < 4; ++j) { va[j] = __builtin_nontemporal_load(xa + 64 * j); vb[j] = __builtin_nontemporal_load(xb + 64 * j); }
; #pragma unroll
;             for (int j = 0; j < 4; ++j) { sa += (va[j][0] * va[j][0] + va[j][1] * va[j][1]) + (va[j][2] * va[j][2] + va[j][3] * va[j][3]); sb += (vb[j][0] * vb[j][0] + vb[j][1] * vb[j][1]) + (vb[j][2] * vb[j][2] + vb[j][3] * vb[j][3]); }
;             const float ra = rsqrtf(wave_sum(sa, x32a) * (1.0f / DM) + 1e-6f), rb = rsqrtf(wave_sum(sb, x32a) * (1.0f / DM) + 1e-6f);
; #pragma unroll
;             for (int j = 0; j < 4; ++j) { xa[64 * j] = (va[j] * ra) * gg[j]; xb[64 * j] = (vb[j] * rb) * gg[j]; }
	v_pk_add_f32 v[56:57], v[56:57], v[58:59]
	s_nop 0
	v_pk_fma_f32 v[56:57], v[56:57], s[8:9], v[206:207] op_sel_hi:[1,0,0]
	s_nop 0
	v_mul_f32_e32 v51, 0x4b800000, v57
	v_cmp_gt_f32_e64 s[40:41], s82, v57
	v_cmp_gt_f32_e32 vcc, s82, v56
	s_nop 0
	v_cndmask_b32_e64 v51, v57, v51, s[40:41]
	v_rsq_f32_e32 v51, v51
	s_nop 0
	v_mul_f32_e32 v57, 0x45800000, v51
	v_cndmask_b32_e64 v58, v51, v57, s[40:41]
	v_mul_f32_e32 v51, 0x4b800000, v56
	v_cndmask_b32_e32 v51, v56, v51, vcc
	v_rsq_f32_e32 v51, v51
	v_pk_mul_f32 v[46:47], v[46:47], v[58:59] op_sel_hi:[1,0]
	v_pk_mul_f32 v[48:49], v[48:49], v[58:59] op_sel_hi:[1,0]
	v_pk_mul_f32 v[38:39], v[38:39], v[58:59] op_sel_hi:[1,0]
	v_mul_f32_e32 v56, 0x45800000, v51
	v_cndmask_b32_e32 v56, v51, v56, vcc
	v_pk_mul_f32 v[42:43], v[42:43], v[56:57] op_sel_hi:[1,0]
	v_pk_mul_f32 v[44:45], v[44:45], v[56:57] op_sel_hi:[1,0]
	v_pk_mul_f32 v[40:41], v[40:41], v[58:59] op_sel_hi:[1,0]
	v_pk_mul_f32 v[34:35], v[34:35], v[56:57] op_sel_hi:[1,0]
	v_pk_mul_f32 v[36:37], v[36:37], v[56:57] op_sel_hi:[1,0]
	v_pk_mul_f32 v[30:31], v[30:31], v[58:59] op_sel_hi:[1,0]
	v_pk_mul_f32 v[32:33], v[32:33], v[58:59] op_sel_hi:[1,0]
	v_pk_mul_f32 v[26:27], v[26:27], v[56:57] op_sel_hi:[1,0]
	v_pk_mul_f32 v[28:29], v[28:29], v[56:57] op_sel_hi:[1,0]
	v_pk_mul_f32 v[22:23], v[22:23], v[58:59] op_sel_hi:[1,0]
	v_pk_mul_f32 v[24:25], v[24:25], v[58:59] op_sel_hi:[1,0]
	v_pk_mul_f32 v[18:19], v[18:19], v[56:57] op_sel_hi:[1,0]
	v_pk_mul_f32 v[20:21], v[20:21], v[56:57] op_sel_hi:[1,0]
	v_pk_mul_f32 v[48:49], v[4:5], v[48:49]
	v_pk_mul_f32 v[46:47], v[2:3], v[46:47]
	v_pk_mul_f32 v[44:45], v[4:5], v[44:45]
	v_pk_mul_f32 v[42:43], v[2:3], v[42:43]
	v_pk_mul_f32 v[40:41], v[8:9], v[40:41]
	v_pk_mul_f32 v[38:39], v[6:7], v[38:39]
	v_pk_mul_f32 v[36:37], v[8:9], v[36:37]
	v_pk_mul_f32 v[34:35], v[6:7], v[34:35]
	v_pk_mul_f32 v[32:33], v[12:13], v[32:33]
	v_pk_mul_f32 v[30:31], v[10:11], v[30:31]
	v_pk_mul_f32 v[28:29], v[12:13], v[28:29]
	v_pk_mul_f32 v[26:27], v[10:11], v[26:27]
	v_pk_mul_f32 v[24:25], v[16:17], v[24:25]
	v_pk_mul_f32 v[22:23], v[14:15], v[22:23]
	v_pk_mul_f32 v[20:21], v[16:17], v[20:21]
	v_pk_mul_f32 v[18:19], v[14:15], v[18:19]
	global_store_dwordx4 v[54:55], v[46:49], off offset:-4096
	global_store_dwordx4 v[54:55], v[42:45], off
	global_store_dwordx4 v[54:55], v[38:41], off offset:-3072
	global_store_dwordx4 v[54:55], v[34:37], off offset:1024
	global_store_dwordx4 v[54:55], v[30:33], off offset:-2048
	global_store_dwordx4 v[54:55], v[26:29], off offset:2048
	global_store_dwordx4 v[54:55], v[22:25], off offset:-1024
	global_store_dwordx4 v[54:55], v[18:21], off offset:3072
	v_lshl_add_u64 v[54:55], v[54:55], 0, s[6:7]
	s_add_i32 s4, s4, 2
	s_cmp_gt_u32 s4, 13
	s_waitcnt vmcnt(8)
	v_pk_mul_f32 v[56:57], v[72:73], v[72:73]
	v_pk_mul_f32 v[58:59], v[70:71], v[70:71]
	s_waitcnt vmcnt(9)
	v_mul_f32_e32 v51, v94, v94
	v_pk_mov_b32 v[60:61], v[58:59], v[56:57] op_sel:[1,0]
	v_mov_b32_e32 v59, v57
	v_pk_add_f32 v[56:57], v[60:61], v[58:59]
	v_pk_mul_f32 v[58:59], v[76:77], v[76:77]
	v_pk_mul_f32 v[60:61], v[74:75], v[74:75]
	v_pk_add_f32 v[56:57], v[56:57], v[56:57] op_sel:[0,1] op_sel_hi:[1,0]
	v_pk_mov_b32 v[62:63], v[60:61], v[58:59] op_sel:[1,0]
	v_mov_b32_e32 v61, v59
	v_pk_add_f32 v[58:59], v[62:63], v[60:61]
	v_pk_mul_f32 v[60:61], v[80:81], v[80:81]
	v_pk_mul_f32 v[62:63], v[78:79], v[78:79]
	v_mov_b32_e32 v57, v51
	v_pk_mov_b32 v[64:65], v[62:63], v[60:61] op_sel:[1,0]
	v_mov_b32_e32 v63, v61
	v_pk_add_f32 v[60:61], v[64:65], v[62:63]
	v_pk_mul_f32 v[62:63], v[84:85], v[84:85]
	v_pk_mul_f32 v[64:65], v[82:83], v[82:83]
	v_pk_add_f32 v[60:61], v[60:61], v[60:61] op_sel:[0,1] op_sel_hi:[1,0]
	v_pk_mov_b32 v[66:67], v[64:65], v[62:63] op_sel:[1,0]
	v_mov_b32_e32 v65, v63
	v_pk_add_f32 v[62:63], v[66:67], v[64:65]
	v_mul_f32_e32 v64, v95, v95
	v_mov_b32_e32 v61, v64
	v_pk_add_f32 v[56:57], v[56:57], v[60:61]
	v_mul_f32_e32 v60, v87, v87
	v_mul_f32_e32 v65, v96, v96
	v_pk_fma_f32 v[60:61], v[86:87], v[86:87], v[60:61] op_sel_hi:[1,1,0]
	v_mul_f32_e32 v64, v89, v89
	v_mul_f32_e32 v66, v97, v97
	v_mov_b32_e32 v61, v65
	v_pk_fma_f32 v[64:65], v[88:89], v[88:89], v[64:65] op_sel_hi:[1,1,0]
	s_waitcnt vmcnt(8)
; __device__ __forceinline__ void final_phase(const Params& p) {
;     ...
;         for (int rr = 0; rr < RPW; rr += 2) {
;             f32x4* xa = (f32x4*)(p.out + (size_t)(r0 + rr) * DM) + lane; f32x4* xb = xa + DM / 4;
;             f32x4 va[4], vb[4]; float sa = 0.f, sb = 0.f;
; #pragma unroll
;             for (int j = 0; j < 4; ++j) { va[j] = __builtin_nontemporal_load(xa + 64 * j); vb[j] = __builtin_nontemporal_load(xb + 64 * j); }
; #pragma unroll
;             for (int j = 0; j < 4; ++j) { sa += (va[j][0] * va[j][0] + va[j][1] * va[j][1]) + (va[j][2] * va[j][2] + va[j][3] * va[j][3]); sb += (vb[j][0] * vb[j][0] + vb[j][1] * vb[j][1]) + (vb[j][2] * vb[j][2] + vb[j][3] * vb[j][3]); }
;             const float ra = rsqrtf(wave_sum(sa, x32a) * (1.0f / DM) + 1e-6f), rb = rsqrtf(wave_sum(sb, x32a) * (1.0f / DM) + 1e-6f);
; #pragma unroll
;             for (int j = 0; j < 4; ++j) { xa[64 * j] = (va[j] * ra) * gg[j]; xb[64 * j] = (vb[j] * rb) * gg[j]; }
;         }
;     }
	v_mul_f32_e32 v51, v98, v98
	v_mov_b32_e32 v65, v66
	v_pk_add_f32 v[60:61], v[60:61], v[64:65]
	v_mul_f32_e32 v64, v99, v99
	v_pk_add_f32 v[56:57], v[56:57], v[60:61]
	v_pk_add_f32 v[58:59], v[58:59], v[58:59] op_sel:[0,1] op_sel_hi:[1,0]
	v_pk_add_f32 v[60:61], v[62:63], v[62:63] op_sel:[0,1] op_sel_hi:[1,0]
	v_mov_b32_e32 v59, v51
	v_mov_b32_e32 v61, v64
	v_pk_add_f32 v[58:59], v[58:59], v[60:61]
	v_mul_f32_e32 v60, v91, v91
	v_mul_f32_e32 v62, v93, v93
	v_mul_f32_e32 v65, v100, v100
	v_mul_f32_e32 v66, v101, v101
	v_pk_fma_f32 v[60:61], v[90:91], v[90:91], v[60:61] op_sel_hi:[1,1,0]
	v_pk_fma_f32 v[62:63], v[92:93], v[92:93], v[62:63] op_sel_hi:[1,1,0]
	v_mov_b32_e32 v61, v65
	v_mov_b32_e32 v63, v66
	v_pk_add_f32 v[60:61], v[60:61], v[62:63]
	s_nop 0
	v_pk_add_f32 v[58:59], v[58:59], v[60:61]
	v_mov_b32_e32 v61, v56
	v_mov_b32_e32 v60, v58
	v_mov_b32_e32 v56, v59
	v_pk_add_f32 v[56:57], v[60:61], v[56:57]
	ds_swizzle_b32 v59, v57 offset:swizzle(SWAP,1)
	ds_swizzle_b32 v58, v56 offset:swizzle(SWAP,1)
	s_waitcnt lgkmcnt(0)
	v_pk_add_f32 v[56:57], v[56:57], v[58:59]
	ds_swizzle_b32 v59, v57 offset:swizzle(SWAP,2)
	ds_swizzle_b32 v58, v56 offset:swizzle(SWAP,2)
	s_waitcnt lgkmcnt(0)
	v_pk_add_f32 v[56:57], v[56:57], v[58:59]
	ds_swizzle_b32 v59, v57 offset:swizzle(SWAP,4)
	ds_swizzle_b32 v58, v56 offset:swizzle(SWAP,4)
	s_waitcnt lgkmcnt(0)
	v_pk_add_f32 v[56:57], v[56:57], v[58:59]
	ds_swizzle_b32 v59, v57 offset:swizzle(SWAP,8)
	ds_swizzle_b32 v58, v56 offset:swizzle(SWAP,8)
	s_waitcnt lgkmcnt(0)
	v_pk_add_f32 v[56:57], v[56:57], v[58:59]
	ds_swizzle_b32 v59, v57 offset:swizzle(SWAP,16)
	ds_swizzle_b32 v58, v56 offset:swizzle(SWAP,16)
	s_waitcnt lgkmcnt(0)
	v_pk_add_f32 v[56:57], v[56:57], v[58:59]
	ds_bpermute_b32 v59, v1, v57
	ds_bpermute_b32 v58, v1, v56
	s_waitcnt lgkmcnt(0)
	v_pk_add_f32 v[56:57], v[56:57], v[58:59]
	s_nop 0
	v_pk_fma_f32 v[56:57], v[56:57], s[8:9], v[206:207] op_sel_hi:[1,0,0]
	s_nop 0
	v_mul_f32_e32 v51, 0x4b800000, v57
	v_cmp_gt_f32_e64 s[40:41], s82, v57
	v_cmp_gt_f32_e32 vcc, s82, v56
	s_nop 0
	v_cndmask_b32_e64 v51, v57, v51, s[40:41]
	v_rsq_f32_e32 v51, v51
	s_nop 0
	v_mul_f32_e32 v57, 0x45800000, v51
	v_cndmask_b32_e64 v58, v51, v57, s[40:41]
	v_mul_f32_e32 v51, 0x4b800000, v56
	v_cndmask_b32_e32 v51, v56, v51, vcc
	v_rsq_f32_e32 v51, v51
	v_pk_mul_f32 v[70:71], v[70:71], v[58:59] op_sel_hi:[1,0]
	v_pk_mul_f32 v[72:73], v[72:73], v[58:59] op_sel_hi:[1,0]
	v_pk_mul_f32 v[78:79], v[78:79], v[58:59] op_sel_hi:[1,0]
	v_mul_f32_e32 v56, 0x45800000, v51
	v_cndmask_b32_e32 v56, v51, v56, vcc
	v_pk_mul_f32 v[74:75], v[74:75], v[56:57] op_sel_hi:[1,0]
	v_pk_mul_f32 v[76:77], v[76:77], v[56:57] op_sel_hi:[1,0]
	v_pk_mul_f32 v[80:81], v[80:81], v[58:59] op_sel_hi:[1,0]
	v_pk_mul_f32 v[82:83], v[82:83], v[56:57] op_sel_hi:[1,0]
	v_pk_mul_f32 v[84:85], v[84:85], v[56:57] op_sel_hi:[1,0]
	v_pk_mul_f32 v[86:87], v[86:87], v[58:59] op_sel_hi:[1,0]
	v_pk_mul_f32 v[88:89], v[88:89], v[58:59] op_sel_hi:[1,0]
	v_pk_mul_f32 v[90:91], v[90:91], v[56:57] op_sel_hi:[1,0]
	v_pk_mul_f32 v[92:93], v[92:93], v[56:57] op_sel_hi:[1,0]
	v_pk_mul_f32 v[94:95], v[94:95], v[58:59] op_sel_hi:[1,0]
	v_pk_mul_f32 v[96:97], v[96:97], v[58:59] op_sel_hi:[1,0]
	v_pk_mul_f32 v[98:99], v[98:99], v[56:57] op_sel_hi:[1,0]
	v_pk_mul_f32 v[100:101], v[100:101], v[56:57] op_sel_hi:[1,0]
	v_pk_mul_f32 v[72:73], v[4:5], v[72:73]
	v_pk_mul_f32 v[70:71], v[2:3], v[70:71]
	v_pk_mul_f32 v[76:77], v[4:5], v[76:77]
	v_pk_mul_f32 v[74:75], v[2:3], v[74:75]
	v_pk_mul_f32 v[80:81], v[8:9], v[80:81]
	v_pk_mul_f32 v[78:79], v[6:7], v[78:79]
	v_pk_mul_f32 v[84:85], v[8:9], v[84:85]
	v_pk_mul_f32 v[82:83], v[6:7], v[82:83]
	v_pk_mul_f32 v[88:89], v[12:13], v[88:89]
	v_pk_mul_f32 v[86:87], v[10:11], v[86:87]
	v_pk_mul_f32 v[92:93], v[12:13], v[92:93]
	v_pk_mul_f32 v[90:91], v[10:11], v[90:91]
	v_pk_mul_f32 v[96:97], v[16:17], v[96:97]
	v_pk_mul_f32 v[94:95], v[14:15], v[94:95]
	v_pk_mul_f32 v[100:101], v[16:17], v[100:101]
	v_pk_mul_f32 v[98:99], v[14:15], v[98:99]
	global_store_dwordx4 v[54:55], v[70:73], off offset:-4096
	global_store_dwordx4 v[54:55], v[74:77], off
	global_store_dwordx4 v[54:55], v[78:81], off offset:-3072
	global_store_dwordx4 v[54:55], v[82:85], off offset:1024
	global_store_dwordx4 v[54:55], v[86:89], off offset:-2048
	global_store_dwordx4 v[54:55], v[90:93], off offset:2048
	global_store_dwordx4 v[54:55], v[94:97], off offset:-1024
	global_store_dwordx4 v[54:55], v[98:101], off offset:3072
	v_lshl_add_u64 v[54:55], v[54:55], 0, s[6:7]
	s_cbranch_scc0 .LBB0_30
	v_readlane_b32 s4, v254, 62
	v_readlane_b32 s5, v254, 63
	s_nop 0
	v_add_u32_e32 v50, s4, v50
	v_readlane_b32 s4, v254, 51
	v_cmp_lt_i32_e32 vcc, s2, v50
	v_readlane_b32 s5, v254, 52
	s_or_b64 s[42:43], vcc, s[42:43]
	s_nop 0
	v_lshl_add_u64 v[52:53], v[52:53], 0, s[4:5]
	s_andn2_b64 exec, exec, s[42:43]
	s_cbranch_execnz .LBB0_29

; __device__ __forceinline__ void norm_phase(const Params& p, int layer) {
;     ...
;         for (int rr = 0; rr < RPW; rr += 2) {
;             const int row = r0 + rr;
;             const f32x4* xa = (const f32x4*)(src + (size_t)row * DM) + lane; const f32x4* xb = xa + DM / 4;
;             f32x4 va[4], vb[4]; float sa = 0.f, sb = 0.f;
; #pragma unroll
;             for (int j = 0; j < 4; ++j) { va[j] = __builtin_nontemporal_load(xa + 64 * j); vb[j] = __builtin_nontemporal_load(xb + 64 * j); }
; #pragma unroll
;             for (int j = 0; j < 4; ++j) { sa += (va[j][0] * va[j][0] + va[j][1] * va[j][1]) + (va[j][2] * va[j][2] + va[j][3] * va[j][3]); sb += (vb[j][0] * vb[j][0] + vb[j][1] * vb[j][1]) + (vb[j][2] * vb[j][2] + vb[j][3] * vb[j][3]); }
;             const float ra = rsqrtf(wave_sum(sa, x32a) * (1.0f / DM) + 1e-6f), rb = rsqrtf(wave_sum(sb, x32a) * (1.0f / DM) + 1e-6f);
.LBB0_415:
	global_load_dwordx4 v[56:59], v[54:55], off offset:-4096 nt
	global_load_dwordx4 v[60:63], v[54:55], off nt
	global_load_dwordx4 v[64:67], v[54:55], off offset:-3072 nt
	global_load_dwordx4 v[70:73], v[54:55], off offset:1024 nt
	global_load_dwordx4 v[102:105], v[54:55], off offset:-2048 nt
	global_load_dwordx4 v[106:109], v[54:55], off offset:-1024 nt
	global_load_dwordx4 v[110:113], v[54:55], off offset:2048 nt
	global_load_dwordx4 v[114:117], v[54:55], off offset:3072 nt
	v_lshl_add_u64 v[150:151], v[54:55], 0, s[6:7]
	global_load_dwordx4 v[118:121], v[150:151], off offset:-4096 nt
	global_load_dwordx4 v[122:125], v[150:151], off nt
	global_load_dwordx4 v[126:129], v[150:151], off offset:-3072 nt
	global_load_dwordx4 v[130:133], v[150:151], off offset:1024 nt
	global_load_dwordx4 v[134:137], v[150:151], off offset:-2048 nt
	global_load_dwordx4 v[138:141], v[150:151], off offset:-1024 nt
	global_load_dwordx4 v[142:145], v[150:151], off offset:2048 nt
	global_load_dwordx4 v[146:149], v[150:151], off offset:3072 nt
	s_waitcnt vmcnt(15)
	v_pk_mul_f32 v[68:69], v[58:59], v[58:59]
	v_pk_mul_f32 v[74:75], v[56:57], v[56:57]
	s_waitcnt vmcnt(14)
	v_pk_mul_f32 v[76:77], v[62:63], v[62:63]
	v_pk_mov_b32 v[78:79], v[74:75], v[68:69] op_sel:[1,0]
	v_mov_b32_e32 v75, v69
	v_pk_mul_f32 v[68:69], v[60:61], v[60:61]
	s_waitcnt vmcnt(13)
	v_pk_mul_f32 v[82:83], v[64:65], v[64:65]
	v_pk_mov_b32 v[80:81], v[68:69], v[76:77] op_sel:[1,0]
	v_mov_b32_e32 v69, v77
	v_pk_mul_f32 v[76:77], v[66:67], v[66:67]
	s_waitcnt vmcnt(12)
	v_pk_mul_f32 v[86:87], v[70:71], v[70:71]
	v_pk_mov_b32 v[84:85], v[82:83], v[76:77] op_sel:[1,0]
	v_mov_b32_e32 v83, v77
	v_pk_mul_f32 v[76:77], v[72:73], v[72:73]
	v_pk_add_f32 v[90:91], v[78:79], v[74:75]
	v_pk_mov_b32 v[88:89], v[86:87], v[76:77] op_sel:[1,0]
	v_mov_b32_e32 v87, v77
	v_pk_add_f32 v[68:69], v[80:81], v[68:69]
	v_pk_add_f32 v[92:93], v[84:85], v[82:83]
	v_pk_add_f32 v[94:95], v[88:89], v[86:87]
	v_pk_add_f32 v[90:91], v[90:91], v[90:91] op_sel:[0,1] op_sel_hi:[1,0]
	v_pk_add_f32 v[92:93], v[92:93], v[92:93] op_sel:[0,1] op_sel_hi:[1,0]
	v_pk_add_f32 v[68:69], v[68:69], v[68:69] op_sel:[0,1] op_sel_hi:[1,0]
	s_waitcnt vmcnt(11)
	v_mul_f32_e32 v82, v103, v103
	v_mul_f32_e32 v84, v105, v105
	v_pk_fma_f32 v[82:83], v[102:103], v[102:103], v[82:83] op_sel_hi:[1,1,0]
	v_pk_fma_f32 v[84:85], v[104:105], v[104:105], v[84:85] op_sel_hi:[1,1,0]
	s_waitcnt vmcnt(10)
	v_mul_f32_e32 v83, v108, v108
	v_mul_f32_e32 v85, v109, v109
	v_pk_add_f32 v[96:97], v[82:83], v[84:85]
	v_mul_f32_e32 v91, v106, v106
	v_mul_f32_e32 v93, v107, v107
	v_pk_add_f32 v[90:91], v[90:91], v[92:93]
	v_pk_add_f32 v[92:93], v[94:95], v[94:95] op_sel:[0,1] op_sel_hi:[1,0]
	v_pk_add_f32 v[90:91], v[90:91], v[96:97]
	v_lshl_add_u64 v[54:55], v[54:55], 0, s[6:7]
	s_waitcnt vmcnt(9)
	v_mul_f32_e32 v98, v111, v111
	v_mul_f32_e32 v100, v113, v113
	v_pk_fma_f32 v[98:99], v[110:111], v[110:111], v[98:99] op_sel_hi:[1,1,0]
	v_pk_fma_f32 v[100:101], v[112:113], v[112:113], v[100:101] op_sel_hi:[1,1,0]
	s_waitcnt vmcnt(8)
	v_mul_f32_e32 v99, v116, v116
	v_mul_f32_e32 v101, v117, v117
	v_mul_f32_e32 v69, v114, v114
	v_mul_f32_e32 v93, v115, v115
	v_pk_add_f32 v[98:99], v[98:99], v[100:101]
	v_pk_add_f32 v[68:69], v[68:69], v[92:93]
	v_mov_b32_e32 v93, v90
	v_pk_add_f32 v[68:69], v[68:69], v[98:99]
	s_nop 0
	v_mov_b32_e32 v92, v68
	v_mov_b32_e32 v90, v69
	v_pk_add_f32 v[68:69], v[92:93], v[90:91]
	ds_swizzle_b32 v91, v69 offset:swizzle(SWAP,1)
	ds_swizzle_b32 v90, v68 offset:swizzle(SWAP,1)
	s_waitcnt lgkmcnt(0)
	v_pk_add_f32 v[68:69], v[68:69], v[90:91]
	ds_swizzle_b32 v91, v69 offset:swizzle(SWAP,2)
	ds_swizzle_b32 v90, v68 offset:swizzle(SWAP,2)
	s_waitcnt lgkmcnt(0)
	v_pk_add_f32 v[68:69], v[68:69], v[90:91]
	ds_swizzle_b32 v91, v69 offset:swizzle(SWAP,4)
	ds_swizzle_b32 v90, v68 offset:swizzle(SWAP,4)
	s_waitcnt lgkmcnt(0)
	v_pk_add_f32 v[68:69], v[68:69], v[90:91]
	ds_swizzle_b32 v91, v69 offset:swizzle(SWAP,8)
	ds_swizzle_b32 v90, v68 offset:swizzle(SWAP,8)
	s_waitcnt lgkmcnt(0)
	v_pk_add_f32 v[68:69], v[68:69], v[90:91]
	ds_swizzle_b32 v91, v69 offset:swizzle(SWAP,16)
	ds_swizzle_b32 v90, v68 offset:swizzle(SWAP,16)
	s_waitcnt lgkmcnt(0)
	v_pk_add_f32 v[68:69], v[68:69], v[90:91]
	ds_bpermute_b32 v91, v1, v69
	ds_bpermute_b32 v90, v1, v68
	s_waitcnt lgkmcnt(0)
; __device__ __forceinline__ unsigned pk_bf16(float lo, float hi) { const f32x2 v = {lo, hi}; const bf16v2 b = __builtin_convertvector(v, bf16v2); return __builtin_bit_cast(unsigned, b); }
; __device__ __forceinline__ void norm_phase(const Params& p, int layer) {
;     ...
;         for (int rr = 0; rr < RPW; rr += 2) {
;             const int row = r0 + rr;
;             const f32x4* xa = (const f32x4*)(src + (size_t)row * DM) + lane; const f32x4* xb = xa + DM / 4;
;             f32x4 va[4], vb[4]; float sa = 0.f, sb = 0.f;
; #pragma unroll
;             for (int j = 0; j < 4; ++j) { va[j] = __builtin_nontemporal_load(xa + 64 * j); vb[j] = __builtin_nontemporal_load(xb + 64 * j); }
; #pragma unroll
;             for (int j = 0; j < 4; ++j) { sa += (va[j][0] * va[j][0] + va[j][1] * va[j][1]) + (va[j][2] * va[j][2] + va[j][3] * va[j][3]); sb += (vb[j][0] * vb[j][0] + vb[j][1] * vb[j][1]) + (vb[j][2] * vb[j][2] + vb[j][3] * vb[j][3]); }
;             const float ra = rsqrtf(wave_sum(sa, x32a) * (1.0f / DM) + 1e-6f), rb = rsqrtf(wave_sum(sb, x32a) * (1.0f / DM) + 1e-6f);
; #pragma unroll
;             for (int j = 0; j < 4; ++j) { const int col = 4 * lane + 256 * j;
;                 const f32x4 ya = (va[j] * ra) * gs[j] + sh[j], yb = (vb[j] * rb) * gs[j] + sh[j];
;                 u32x2 wa, wb; wa.x = pk_bf16(ya[0], ya[1]); wa.y = pk_bf16(ya[2], ya[3]); wb.x = pk_bf16(yb[0], yb[1]); wb.y = pk_bf16(yb[2], yb[3]);
;                 *(u32x2*)(H + (size_t)row * DM + col) = wa; *(u32x2*)(H + (size_t)(row + 1) * DM + col) = wb; }
	v_pk_add_f32 v[68:69], v[68:69], v[90:91]
	s_nop 0
	v_pk_fma_f32 v[90:91], v[68:69], s[8:9], v[206:207] op_sel_hi:[1,0,0]
	s_nop 0
	v_mul_f32_e32 v19, 0x4b800000, v91
	v_cmp_gt_f32_e32 vcc, s82, v91
	s_nop 1
	v_cndmask_b32_e32 v19, v91, v19, vcc
	v_rsq_f32_e32 v19, v19
	s_nop 0
	v_mul_f32_e32 v29, 0x45800000, v19
	v_cndmask_b32_e32 v68, v19, v29, vcc
	v_mul_f32_e32 v19, 0x4b800000, v90
	v_cmp_gt_f32_e32 vcc, s82, v90
	v_pk_mul_f32 v[56:57], v[56:57], v[68:69] op_sel_hi:[1,0]
	v_pk_mul_f32 v[58:59], v[58:59], v[68:69] op_sel_hi:[1,0]
	v_cndmask_b32_e32 v19, v90, v19, vcc
	v_rsq_f32_e32 v19, v19
	v_pk_mul_f32 v[94:95], v[102:103], v[68:69] op_sel_hi:[1,0]
	v_pk_fma_f32 v[58:59], v[36:37], v[58:59], v[4:5]
	v_pk_fma_f32 v[56:57], v[38:39], v[56:57], v[2:3]
	v_mul_f32_e32 v29, 0x45800000, v19
	v_cndmask_b32_e32 v74, v19, v29, vcc
	v_pk_mul_f32 v[60:61], v[60:61], v[74:75] op_sel_hi:[1,0]
	v_pk_mul_f32 v[62:63], v[62:63], v[74:75] op_sel_hi:[1,0]
	v_pk_mul_f32 v[64:65], v[64:65], v[68:69] op_sel_hi:[1,0]
	v_pk_mul_f32 v[92:93], v[66:67], v[68:69] op_sel_hi:[1,0]
	v_cvt_pk_bf16_f32 v56, v56, v57
	v_cvt_pk_bf16_f32 v57, v58, v59
	v_pk_fma_f32 v[62:63], v[36:37], v[62:63], v[4:5]
	v_pk_fma_f32 v[58:59], v[38:39], v[60:61], v[2:3]
	v_pk_mul_f32 v[96:97], v[104:105], v[68:69] op_sel_hi:[1,0]
	v_pk_mul_f32 v[66:67], v[106:107], v[68:69] op_sel_hi:[1,0]
	v_pk_mul_f32 v[68:69], v[108:109], v[68:69] op_sel_hi:[1,0]
	v_pk_mul_f32 v[78:79], v[70:71], v[74:75] op_sel_hi:[1,0]
	v_pk_mul_f32 v[80:81], v[72:73], v[74:75] op_sel_hi:[1,0]
	v_cvt_pk_bf16_f32 v58, v58, v59
	v_cvt_pk_bf16_f32 v59, v62, v63
	v_pk_fma_f32 v[62:63], v[40:41], v[92:93], v[12:13]
	v_pk_fma_f32 v[60:61], v[42:43], v[64:65], v[10:11]
	v_pk_fma_f32 v[64:65], v[40:41], v[80:81], v[12:13]
	v_cvt_pk_bf16_f32 v60, v60, v61
	v_cvt_pk_bf16_f32 v61, v62, v63
	v_pk_fma_f32 v[62:63], v[42:43], v[78:79], v[10:11]
	v_pk_fma_f32 v[78:79], v[44:45], v[96:97], v[16:17]
	v_cvt_pk_bf16_f32 v62, v62, v63
	v_cvt_pk_bf16_f32 v63, v64, v65
	v_pk_fma_f32 v[64:65], v[46:47], v[94:95], v[14:15]
	v_pk_mul_f32 v[72:73], v[110:111], v[74:75] op_sel_hi:[1,0]
	v_cvt_pk_bf16_f32 v64, v64, v65
	v_cvt_pk_bf16_f32 v65, v78, v79
	v_add3_u32 v78, v18, s4, 3
	v_pk_mul_f32 v[76:77], v[112:113], v[74:75] op_sel_hi:[1,0]
	v_pk_mul_f32 v[70:71], v[114:115], v[74:75] op_sel_hi:[1,0]
	v_pk_mul_f32 v[74:75], v[116:117], v[74:75] op_sel_hi:[1,0]
	v_ashrrev_i32_e32 v79, 31, v78
	s_add_i32 s4, s4, 2
	v_lshlrev_b64 v[78:79], 11, v[78:79]
	v_pk_fma_f32 v[76:77], v[44:45], v[76:77], v[16:17]
	v_pk_fma_f32 v[72:73], v[46:47], v[72:73], v[14:15]
	v_pk_fma_f32 v[68:69], v[48:49], v[68:69], v[8:9]
	v_pk_fma_f32 v[66:67], v[50:51], v[66:67], v[6:7]
	v_pk_fma_f32 v[74:75], v[48:49], v[74:75], v[8:9]
	v_pk_fma_f32 v[70:71], v[50:51], v[70:71], v[6:7]
	s_cmp_gt_u32 s4, 13
	v_lshl_add_u64 v[78:79], v[22:23], 0, v[78:79]
	v_cvt_pk_bf16_f32 v72, v72, v73
	v_cvt_pk_bf16_f32 v73, v76, v77
	v_cvt_pk_bf16_f32 v66, v66, v67
	v_cvt_pk_bf16_f32 v67, v68, v69
	v_cvt_pk_bf16_f32 v68, v70, v71
	v_cvt_pk_bf16_f32 v69, v74, v75
	global_store_dwordx2 v[52:53], v[56:57], off offset:-1024
	global_store_dwordx2 v[78:79], v[58:59], off
	global_store_dwordx2 v[52:53], v[60:61], off offset:-512
	global_store_dwordx2 v[78:79], v[62:63], off offset:512
	global_store_dwordx2 v[52:53], v[64:65], off
	global_store_dwordx2 v[78:79], v[72:73], off offset:1024
	global_store_dwordx2 v[52:53], v[66:67], off offset:512
	global_store_dwordx2 v[78:79], v[68:69], off offset:1536
	v_lshl_add_u64 v[52:53], v[52:53], 0, s[98:99]
	s_waitcnt vmcnt(15)
	v_pk_mul_f32 v[68:69], v[120:121], v[120:121]
	v_pk_mul_f32 v[74:75], v[118:119], v[118:119]
	s_waitcnt vmcnt(14)
	v_pk_mul_f32 v[76:77], v[124:125], v[124:125]
	v_pk_mov_b32 v[78:79], v[74:75], v[68:69] op_sel:[1,0]
	v_mov_b32_e32 v75, v69
	v_pk_mul_f32 v[68:69], v[122:123], v[122:123]
	s_waitcnt vmcnt(13)
	v_pk_mul_f32 v[82:83], v[126:127], v[126:127]
	v_pk_mov_b32 v[80:81], v[68:69], v[76:77] op_sel:[1,0]
	v_mov_b32_e32 v69, v77
	v_pk_mul_f32 v[76:77], v[128:129], v[128:129]
	s_waitcnt vmcnt(12)
	v_pk_mul_f32 v[86:87], v[130:131], v[130:131]
	v_pk_mov_b32 v[84:85], v[82:83], v[76:77] op_sel:[1,0]
	v_mov_b32_e32 v83, v77
	v_pk_mul_f32 v[76:77], v[132:133], v[132:133]
	v_pk_add_f32 v[90:91], v[78:79], v[74:75]
	v_pk_mov_b32 v[88:89], v[86:87], v[76:77] op_sel:[1,0]
	v_mov_b32_e32 v87, v77
	v_pk_add_f32 v[68:69], v[80:81], v[68:69]
	v_pk_add_f32 v[92:93], v[84:85], v[82:83]
	v_pk_add_f32 v[94:95], v[88:89], v[86:87]
	v_pk_add_f32 v[90:91], v[90:91], v[90:91] op_sel:[0,1] op_sel_hi:[1,0]
	v_pk_add_f32 v[92:93], v[92:93], v[92:93] op_sel:[0,1] op_sel_hi:[1,0]
	v_pk_add_f32 v[68:69], v[68:69], v[68:69] op_sel:[0,1] op_sel_hi:[1,0]
	s_waitcnt vmcnt(11)
	v_mul_f32_e32 v82, v135, v135
	v_mul_f32_e32 v84, v137, v137
	v_pk_fma_f32 v[82:83], v[134:135], v[134:135], v[82:83] op_sel_hi:[1,1,0]
	v_pk_fma_f32 v[84:85], v[136:137], v[136:137], v[84:85] op_sel_hi:[1,1,0]
	s_waitcnt vmcnt(10)
	v_mul_f32_e32 v83, v140, v140
	v_mul_f32_e32 v85, v141, v141
	v_pk_add_f32 v[96:97], v[82:83], v[84:85]
	v_mul_f32_e32 v91, v138, v138
	v_mul_f32_e32 v93, v139, v139
	v_pk_add_f32 v[90:91], v[90:91], v[92:93]
	v_pk_add_f32 v[92:93], v[94:95], v[94:95] op_sel:[0,1] op_sel_hi:[1,0]
	v_pk_add_f32 v[90:91], v[90:91], v[96:97]
	v_lshl_add_u64 v[54:55], v[54:55], 0, s[6:7]
	s_waitcnt vmcnt(9)
	v_mul_f32_e32 v98, v143, v143
	v_mul_f32_e32 v100, v145, v145
	v_pk_fma_f32 v[98:99], v[142:143], v[142:143], v[98:99] op_sel_hi:[1,1,0]
	v_pk_fma_f32 v[100:101], v[144:145], v[144:145], v[100:101] op_sel_hi:[1,1,0]
	s_waitcnt vmcnt(8)
; __device__ __forceinline__ unsigned pk_bf16(float lo, float hi) { const f32x2 v = {lo, hi}; const bf16v2 b = __builtin_convertvector(v, bf16v2); return __builtin_bit_cast(unsigned, b); }
; __device__ __forceinline__ void norm_phase(const Params& p, int layer) {
;     ...
;             const float ra = rsqrtf(wave_sum(sa, x32a) * (1.0f / DM) + 1e-6f), rb = rsqrtf(wave_sum(sb, x32a) * (1.0f / DM) + 1e-6f);
; #pragma unroll
;             for (int j = 0; j < 4; ++j) { const int col = 4 * lane + 256 * j;
;                 const f32x4 ya = (va[j] * ra) * gs[j] + sh[j], yb = (vb[j] * rb) * gs[j] + sh[j];
;                 u32x2 wa, wb; wa.x = pk_bf16(ya[0], ya[1]); wa.y = pk_bf16(ya[2], ya[3]); wb.x = pk_bf16(yb[0], yb[1]); wb.y = pk_bf16(yb[2], yb[3]);
;                 *(u32x2*)(H + (size_t)row * DM + col) = wa; *(u32x2*)(H + (size_t)(row + 1) * DM + col) = wb; }
;         }
;     }
	v_mul_f32_e32 v99, v148, v148
	v_mul_f32_e32 v101, v149, v149
	v_mul_f32_e32 v69, v146, v146
	v_mul_f32_e32 v93, v147, v147
	v_pk_add_f32 v[98:99], v[98:99], v[100:101]
	v_pk_add_f32 v[68:69], v[68:69], v[92:93]
	v_mov_b32_e32 v93, v90
	v_pk_add_f32 v[68:69], v[68:69], v[98:99]
	s_nop 0
	v_mov_b32_e32 v92, v68
	v_mov_b32_e32 v90, v69
	v_pk_add_f32 v[68:69], v[92:93], v[90:91]
	ds_swizzle_b32 v91, v69 offset:swizzle(SWAP,1)
	ds_swizzle_b32 v90, v68 offset:swizzle(SWAP,1)
	s_waitcnt lgkmcnt(0)
	v_pk_add_f32 v[68:69], v[68:69], v[90:91]
	ds_swizzle_b32 v91, v69 offset:swizzle(SWAP,2)
	ds_swizzle_b32 v90, v68 offset:swizzle(SWAP,2)
	s_waitcnt lgkmcnt(0)
	v_pk_add_f32 v[68:69], v[68:69], v[90:91]
	ds_swizzle_b32 v91, v69 offset:swizzle(SWAP,4)
	ds_swizzle_b32 v90, v68 offset:swizzle(SWAP,4)
	s_waitcnt lgkmcnt(0)
	v_pk_add_f32 v[68:69], v[68:69], v[90:91]
	ds_swizzle_b32 v91, v69 offset:swizzle(SWAP,8)
	ds_swizzle_b32 v90, v68 offset:swizzle(SWAP,8)
	s_waitcnt lgkmcnt(0)
	v_pk_add_f32 v[68:69], v[68:69], v[90:91]
	ds_swizzle_b32 v91, v69 offset:swizzle(SWAP,16)
	ds_swizzle_b32 v90, v68 offset:swizzle(SWAP,16)
	s_waitcnt lgkmcnt(0)
	v_pk_add_f32 v[68:69], v[68:69], v[90:91]
	ds_bpermute_b32 v91, v1, v69
	ds_bpermute_b32 v90, v1, v68
	s_waitcnt lgkmcnt(0)
	v_pk_add_f32 v[68:69], v[68:69], v[90:91]
	s_nop 0
	v_pk_fma_f32 v[90:91], v[68:69], s[8:9], v[206:207] op_sel_hi:[1,0,0]
	s_nop 0
	v_mul_f32_e32 v19, 0x4b800000, v91
	v_cmp_gt_f32_e32 vcc, s82, v91
	s_nop 1
	v_cndmask_b32_e32 v19, v91, v19, vcc
	v_rsq_f32_e32 v19, v19
	s_nop 0
	v_mul_f32_e32 v29, 0x45800000, v19
	v_cndmask_b32_e32 v68, v19, v29, vcc
	v_mul_f32_e32 v19, 0x4b800000, v90
	v_cmp_gt_f32_e32 vcc, s82, v90
	v_pk_mul_f32 v[118:119], v[118:119], v[68:69] op_sel_hi:[1,0]
	v_pk_mul_f32 v[120:121], v[120:121], v[68:69] op_sel_hi:[1,0]
	v_cndmask_b32_e32 v19, v90, v19, vcc
	v_rsq_f32_e32 v19, v19
	v_pk_mul_f32 v[94:95], v[134:135], v[68:69] op_sel_hi:[1,0]
	v_pk_fma_f32 v[120:121], v[36:37], v[120:121], v[4:5]
	v_pk_fma_f32 v[118:119], v[38:39], v[118:119], v[2:3]
	v_mul_f32_e32 v29, 0x45800000, v19
	v_cndmask_b32_e32 v74, v19, v29, vcc
	v_pk_mul_f32 v[122:123], v[122:123], v[74:75] op_sel_hi:[1,0]
	v_pk_mul_f32 v[124:125], v[124:125], v[74:75] op_sel_hi:[1,0]
	v_pk_mul_f32 v[126:127], v[126:127], v[68:69] op_sel_hi:[1,0]
	v_pk_mul_f32 v[92:93], v[128:129], v[68:69] op_sel_hi:[1,0]
	v_cvt_pk_bf16_f32 v118, v118, v119
	v_cvt_pk_bf16_f32 v119, v120, v121
	v_pk_fma_f32 v[124:125], v[36:37], v[124:125], v[4:5]
	v_pk_fma_f32 v[120:121], v[38:39], v[122:123], v[2:3]
	v_pk_mul_f32 v[96:97], v[136:137], v[68:69] op_sel_hi:[1,0]
	v_pk_mul_f32 v[128:129], v[138:139], v[68:69] op_sel_hi:[1,0]
	v_pk_mul_f32 v[68:69], v[140:141], v[68:69] op_sel_hi:[1,0]
	v_pk_mul_f32 v[78:79], v[130:131], v[74:75] op_sel_hi:[1,0]
	v_pk_mul_f32 v[80:81], v[132:133], v[74:75] op_sel_hi:[1,0]
	v_cvt_pk_bf16_f32 v120, v120, v121
	v_cvt_pk_bf16_f32 v121, v124, v125
	v_pk_fma_f32 v[124:125], v[40:41], v[92:93], v[12:13]
	v_pk_fma_f32 v[122:123], v[42:43], v[126:127], v[10:11]
	v_pk_fma_f32 v[126:127], v[40:41], v[80:81], v[12:13]
	v_cvt_pk_bf16_f32 v122, v122, v123
	v_cvt_pk_bf16_f32 v123, v124, v125
	v_pk_fma_f32 v[124:125], v[42:43], v[78:79], v[10:11]
	v_pk_fma_f32 v[78:79], v[44:45], v[96:97], v[16:17]
	v_cvt_pk_bf16_f32 v124, v124, v125
	v_cvt_pk_bf16_f32 v125, v126, v127
	v_pk_fma_f32 v[126:127], v[46:47], v[94:95], v[14:15]
	v_pk_mul_f32 v[132:133], v[142:143], v[74:75] op_sel_hi:[1,0]
	v_cvt_pk_bf16_f32 v126, v126, v127
	v_cvt_pk_bf16_f32 v127, v78, v79
	v_add3_u32 v78, v18, s4, 3
	v_pk_mul_f32 v[76:77], v[144:145], v[74:75] op_sel_hi:[1,0]
	v_pk_mul_f32 v[130:131], v[146:147], v[74:75] op_sel_hi:[1,0]
	v_pk_mul_f32 v[74:75], v[148:149], v[74:75] op_sel_hi:[1,0]
	v_ashrrev_i32_e32 v79, 31, v78
	s_add_i32 s4, s4, 2
	v_lshlrev_b64 v[78:79], 11, v[78:79]
	v_pk_fma_f32 v[76:77], v[44:45], v[76:77], v[16:17]
	v_pk_fma_f32 v[132:133], v[46:47], v[132:133], v[14:15]
	v_pk_fma_f32 v[68:69], v[48:49], v[68:69], v[8:9]
	v_pk_fma_f32 v[128:129], v[50:51], v[128:129], v[6:7]
	v_pk_fma_f32 v[74:75], v[48:49], v[74:75], v[8:9]
	v_pk_fma_f32 v[130:131], v[50:51], v[130:131], v[6:7]
	s_cmp_gt_u32 s4, 13
	v_lshl_add_u64 v[78:79], v[22:23], 0, v[78:79]
	v_cvt_pk_bf16_f32 v132, v132, v133
	v_cvt_pk_bf16_f32 v133, v76, v77
	v_cvt_pk_bf16_f32 v128, v128, v129
	v_cvt_pk_bf16_f32 v129, v68, v69
	v_cvt_pk_bf16_f32 v68, v130, v131
	v_cvt_pk_bf16_f32 v69, v74, v75
	global_store_dwordx2 v[52:53], v[118:119], off offset:-1024
	global_store_dwordx2 v[78:79], v[120:121], off
	global_store_dwordx2 v[52:53], v[122:123], off offset:-512
	global_store_dwordx2 v[78:79], v[124:125], off offset:512
	global_store_dwordx2 v[52:53], v[126:127], off
	global_store_dwordx2 v[78:79], v[132:133], off offset:1024
	global_store_dwordx2 v[52:53], v[128:129], off offset:512
	global_store_dwordx2 v[78:79], v[68:69], off offset:1536
	v_lshl_add_u64 v[52:53], v[52:53], 0, s[98:99]
	s_cbranch_scc0 .LBB0_415
	v_readlane_b32 s4, v254, 62
	v_readlane_b32 s5, v254, 63
	s_nop 0
	v_add_u32_e32 v18, s4, v18
	v_readlane_b32 s4, v254, 51
	v_readlane_b32 s5, v254, 52
	v_cmp_lt_i32_e32 vcc, s2, v18
	s_or_b64 s[40:41], vcc, s[40:41]
	v_lshl_add_u64 v[24:25], v[24:25], 0, s[4:5]
	v_readlane_b32 s4, v255, 0
	v_readlane_b32 s5, v255, 1
	s_nop 1
	v_lshl_add_u64 v[26:27], v[26:27], 0, s[4:5]
	s_andn2_b64 exec, exec, s[40:41]
	s_cbranch_execnz .LBB0_414
